# attention QK block: in-place accumulate chains (SrcC == vDst), chain halves four issues apart, K-fragment reloads without MFMA-D wait states
# baseline (speedup 1.0000x reference)
.LBB0_790:
	s_waitcnt lgkmcnt(3)
	v_mfma_f32_16x16x32_bf16 v[192:195], v[144:147], v[72:75], v[228:231]
	v_mfma_f32_16x16x32_bf16 v[180:183], v[144:147], v[84:87], v[232:235]
	v_mfma_f32_16x16x32_bf16 v[156:159], v[144:147], v[100:103], v[248:251]
	v_mfma_f32_16x16x32_bf16 v[152:155], v[144:147], v[108:111], v[220:223]
	s_mov_b32 s6, s53
	s_add_i32 s53, s53, 1
	s_cmp_ge_u32 s53, s52
	s_cselect_b64 s[34:35], -1, 0
	s_cmp_lt_u32 s53, s52
	s_cselect_b32 s6, s53, s6
	s_waitcnt lgkmcnt(2)
	v_mfma_f32_16x16x32_bf16 v[192:195], v[148:151], v[76:79], v[192:195]
	v_mfma_f32_16x16x32_bf16 v[180:183], v[148:151], v[88:91], v[180:183]
	v_mfma_f32_16x16x32_bf16 v[156:159], v[148:151], v[104:107], v[156:159]
	v_mfma_f32_16x16x32_bf16 v[152:155], v[148:151], v[112:115], v[152:155]
	v_lshl_or_b32 v37, s6, 5, v201
	v_mad_u32_u24 v38, v37, s3, v32
	s_waitcnt lgkmcnt(1)
	v_mfma_f32_16x16x32_bf16 v[196:199], v[140:143], v[72:75], v[228:231]
	v_mfma_f32_16x16x32_bf16 v[188:191], v[140:143], v[84:87], v[232:235]
	v_mfma_f32_16x16x32_bf16 v[184:187], v[140:143], v[100:103], v[248:251]
	v_mfma_f32_16x16x32_bf16 v[172:175], v[140:143], v[108:111], v[220:223]
	ds_read_b128 v[144:147], v38
	ds_read_b128 v[148:151], v38 offset:64
	s_waitcnt lgkmcnt(2)
	v_mfma_f32_16x16x32_bf16 v[196:199], v[136:139], v[76:79], v[196:199]
	v_mfma_f32_16x16x32_bf16 v[188:191], v[136:139], v[88:91], v[188:191]
	v_mfma_f32_16x16x32_bf16 v[184:187], v[136:139], v[104:107], v[184:187]
	v_mfma_f32_16x16x32_bf16 v[172:175], v[136:139], v[112:115], v[172:175]
	ds_read_b128 v[140:143], v38 offset:2304
	ds_read_b128 v[136:139], v38 offset:2368
	ds_read_b64_tr_b16 v[168:169], v35
	ds_read_b64_tr_b16 v[170:171], v35 offset:2560
	ds_read_b64_tr_b16 v[160:161], v35 offset:32
	ds_read_b64_tr_b16 v[162:163], v35 offset:2592
	ds_read_b64_tr_b16 v[176:177], v35 offset:64
	ds_read_b64_tr_b16 v[178:179], v35 offset:2624
	ds_read_b64_tr_b16 v[164:165], v35 offset:96
	ds_read_b64_tr_b16 v[166:167], v35 offset:2656
	s_andn2_b64 vcc, exec, s[86:87]
	s_cbranch_vccnz .LBB0_792
